# v019 + SwiGLU slot loads split: row groups 0-3 requested inside the last K iteration (before the final MFMA block, v240-255), groups 4-7 after the loop; rstd computed in two batches of four so the sec
# speedup vs baseline: 1.0020x; 1.0020x over previous
; #define PG8_STAGE(bufoff, gbase, voff) do { _Pragma("unroll") for (int _i = 0; _i < 2; ++_i) \
;         __builtin_amdgcn_global_load_lds((const unsigned*)((const char*)(gbase) + (voff)[_i]), (PG8_LAS unsigned*)(lds + (bufoff) + ldsw + _i * 8192), 16, 0, PG8_LOAD_AUX); } while (0)
; #define PG8_LDA(dst, b, h) do { _Pragma("unroll") for (int m = 0; m < 4; ++m) _Pragma("unroll") for (int k = 0; k < 2; ++k) dst[m][k] = *(const PG8_LAS bf16x8*)(lds + PG8_SA(b, h) + aoff + m * 2048 + k * 1024); } while (0)
; #define PG8_LDB(dst, b, h) do { _Pragma("unroll") for (int n = 0; n < 2; ++n) _Pragma("unroll") for (int k = 0; k < 2; ++k) dst[n][k] = *(const PG8_LAS bf16x8*)(lds + PG8_SB(b, h) + boff + n * 2048 + k * 1024); } while (0)
; #define PG8_MMA(ai, bj, At, Bt) do { __builtin_amdgcn_s_setprio(1); _Pragma("unroll") for (int m = 0; m < 4; ++m) _Pragma("unroll") for (int n = 0; n < 2; ++n) _Pragma("unroll") for (int k = 0; k < 2; ++k) \
;         acc[ai][bj][m][n] = __builtin_amdgcn_mfma_f32_16x16x32_bf16(Bt[n][k], At[m][k], acc[ai][bj][m][n], 0, 0, 0); __builtin_amdgcn_s_setprio(0); } while (0)
; #define PG8_WAIT_V(n) asm volatile("s_waitcnt vmcnt(" #n ")" ::: "memory")
; #define PG8_WAIT_L(n) asm volatile("s_waitcnt lgkmcnt(" #n ")" ::: "memory")
; #define PG8_BAR __builtin_amdgcn_s_barrier()
; #define PG8_SCHED __builtin_amdgcn_sched_barrier(0)
; __device__ __forceinline__ float rstd_from_slots(const float* slots, int row, int fq) {
;     const f32x4 s4 = *(const f32x4*)(slots + (size_t)row * 16 + 4 * fq);
; template <class Epi, class Sched, bool ALIGN_EPI = false, bool SP2 = false>
; __device__ __forceinline__ void gemm_phase(PG8_LAS unsigned char* lds, const Gemm g, const Sched& S, const Epi& E) {
;     ...
;             PG8_LDB(B0, 1, 0); PG8_LDB(B1, 1, 1); PG8_SCHED; PG8_LDA(At, 1, 0); PG8_STAGE(PG8_SA(0, 1), a2 + hstepA, voffA);
;             PG8_WAIT_V(8); PG8_WAIT_L(0); PG8_BAR; PG8_MMA(0, 0, At, B0); PG8_MMA(0, 1, At, B1); PG8_BAR; PG8_SCHED;
;             PG8_LDA(At, 1, 1); PG8_STAGE(PG8_SB(1, 0), b3, voffB); PG8_STAGE(PG8_SB(1, 1), b3 + hstepB, voffB); PG8_STAGE(PG8_SA(1, 0), a3, voffA);
;             PG8_WAIT_V(8); PG8_WAIT_L(0); PG8_BAR; PG8_MMA(1, 0, At, B0); PG8_MMA(1, 1, At, B1); PG8_BAR; PG8_SCHED;
.Lkmid_P7:
	s_add_i32 s29, 0, 0x18000
	v_add_u32_e32 v163, s29, v156
	s_add_i32 s33, 0, 0x1c000
	ds_read_b128 v[146:149], v163
	ds_read_b128 v[164:167], v163 offset:1024
	ds_read_b128 v[168:171], v163 offset:2048
	ds_read_b128 v[172:175], v163 offset:3072
	v_add_u32_e32 v163, s33, v156
	ds_read_b128 v[176:179], v163
	ds_read_b128 v[180:183], v163 offset:1024
	ds_read_b128 v[184:187], v163 offset:2048
	ds_read_b128 v[188:191], v163 offset:3072
	s_add_u32 s30, s34, 0x40000
	s_addc_u32 s31, s35, 0
	s_mov_b32 m0, s47
	v_lshl_add_u64 v[230:231], s[30:31], 0, v[128:129]
	ds_read_b128 v[192:195], v160 offset:32768
	ds_read_b128 v[196:199], v160 offset:33792
	ds_read_b128 v[200:203], v160 offset:34816
	ds_read_b128 v[204:207], v160 offset:35840
	ds_read_b128 v[208:211], v160 offset:36864
	ds_read_b128 v[212:215], v160 offset:37888
	ds_read_b128 v[216:219], v160 offset:38912
	ds_read_b128 v[220:223], v160 offset:39936
	global_load_lds_dwordx4 v[230:231], off
	v_lshl_add_u64 v[230:231], s[30:31], 0, v[132:133]
	s_mov_b32 m0, s48
	s_nop 0
	global_load_lds_dwordx4 v[230:231], off
	s_waitcnt vmcnt(8)
	s_waitcnt lgkmcnt(0)
	s_barrier
	s_waitcnt lgkmcnt(0)
	v_mfma_f32_16x16x32_bf16 v[124:127], v[146:149], v[192:195], v[124:127]
	v_mfma_f32_16x16x32_bf16 v[120:123], v[168:171], v[192:195], v[120:123]
	v_mfma_f32_16x16x32_bf16 v[108:111], v[146:149], v[200:203], v[108:111]
	v_mfma_f32_16x16x32_bf16 v[104:107], v[168:171], v[200:203], v[104:107]
	v_mfma_f32_16x16x32_bf16 v[92:95], v[146:149], v[208:211], v[92:95]
	v_mfma_f32_16x16x32_bf16 v[88:91], v[168:171], v[208:211], v[88:91]
	v_mfma_f32_16x16x32_bf16 v[76:79], v[146:149], v[216:219], v[76:79]
	v_mfma_f32_16x16x32_bf16 v[72:75], v[168:171], v[216:219], v[72:75]
	v_mfma_f32_16x16x32_bf16 v[124:127], v[164:167], v[196:199], v[124:127]
	v_mfma_f32_16x16x32_bf16 v[120:123], v[172:175], v[196:199], v[120:123]
	v_mfma_f32_16x16x32_bf16 v[108:111], v[164:167], v[204:207], v[108:111]
	v_mfma_f32_16x16x32_bf16 v[104:107], v[172:175], v[204:207], v[104:107]
	v_mfma_f32_16x16x32_bf16 v[92:95], v[164:167], v[212:215], v[92:95]
	v_mfma_f32_16x16x32_bf16 v[88:91], v[172:175], v[212:215], v[88:91]
	v_mfma_f32_16x16x32_bf16 v[76:79], v[164:167], v[220:223], v[76:79]
	v_mfma_f32_16x16x32_bf16 v[72:75], v[172:175], v[220:223], v[72:75]
	v_mfma_f32_16x16x32_bf16 v[116:119], v[176:179], v[192:195], v[116:119]
	v_mfma_f32_16x16x32_bf16 v[112:115], v[184:187], v[192:195], v[112:115]
	v_mfma_f32_16x16x32_bf16 v[100:103], v[176:179], v[200:203], v[100:103]
	v_mfma_f32_16x16x32_bf16 v[96:99], v[184:187], v[200:203], v[96:99]
	v_mfma_f32_16x16x32_bf16 v[84:87], v[176:179], v[208:211], v[84:87]
	v_mfma_f32_16x16x32_bf16 v[80:83], v[184:187], v[208:211], v[80:83]
	v_mfma_f32_16x16x32_bf16 v[68:71], v[176:179], v[216:219], v[68:71]
	v_mfma_f32_16x16x32_bf16 v[64:67], v[184:187], v[216:219], v[64:67]
	v_mfma_f32_16x16x32_bf16 v[116:119], v[180:183], v[196:199], v[116:119]
	v_mfma_f32_16x16x32_bf16 v[112:115], v[188:191], v[196:199], v[112:115]
	v_mfma_f32_16x16x32_bf16 v[100:103], v[180:183], v[204:207], v[100:103]
	v_mfma_f32_16x16x32_bf16 v[96:99], v[188:191], v[204:207], v[96:99]
	v_mfma_f32_16x16x32_bf16 v[84:87], v[180:183], v[212:215], v[84:87]
	v_mfma_f32_16x16x32_bf16 v[80:83], v[188:191], v[212:215], v[80:83]
	v_mfma_f32_16x16x32_bf16 v[68:71], v[180:183], v[220:223], v[68:71]
	v_mfma_f32_16x16x32_bf16 v[64:67], v[188:191], v[220:223], v[64:67]
	s_barrier
	s_add_i32 s29, s29, s40
	v_lshl_add_u64 v[150:151], v[150:151], 0, s[8:9]
	s_mov_b32 m0, s29
	ds_read_b128 v[192:195], v160 offset:49152
	ds_read_b128 v[196:199], v160 offset:50176
	ds_read_b128 v[200:203], v160 offset:51200
	ds_read_b128 v[204:207], v160 offset:52224
	ds_read_b128 v[208:211], v160 offset:53248
	ds_read_b128 v[212:215], v160 offset:54272
	ds_read_b128 v[216:219], v160 offset:55296
	ds_read_b128 v[220:223], v160 offset:56320
	global_load_lds_dwordx4 v[150:151], off
	s_add_i32 m0, s29, 0x2000
	s_add_u32 s22, s22, 0x40080
	v_lshl_add_u64 v[150:151], v[224:225], 0, s[8:9]
	s_addc_u32 s23, s23, 0
	s_add_i32 s29, s33, s40
	global_load_lds_dwordx4 v[150:151], off
	v_lshl_add_u64 v[150:151], s[22:23], 0, v[130:131]
	s_mov_b32 m0, s29
	s_nop 0
	global_load_lds_dwordx4 v[150:151], off
	v_lshl_add_u64 v[150:151], s[22:23], 0, v[134:135]
	s_add_i32 m0, s29, 0x2000
	s_nop 0
	global_load_lds_dwordx4 v[150:151], off
	v_lshl_add_u64 v[150:151], v[226:227], 0, s[8:9]
	s_mov_b32 m0, s51
	s_nop 0
	global_load_lds_dwordx4 v[150:151], off
	v_lshl_add_u64 v[150:151], v[228:229], 0, s[8:9]
	s_mov_b32 m0, s52
	s_nop 0
	global_load_lds_dwordx4 v[150:151], off
	s_waitcnt vmcnt(8)
	s_waitcnt lgkmcnt(0)
	s_cmp_lt_i32 s28, 12
	s_cbranch_scc1 .Lnoslot_P7
	v_lshl_add_u32 v232, s0, 8, v152
	v_ashrrev_i32_e32 v233, 31, v232
	v_lshlrev_b64 v[232:233], 6, v[232:233]
	v_lshl_add_u64 v[232:233], v[136:137], 0, v[232:233]
	global_load_dwordx4 v[240:243], v[232:233], off
	global_load_dwordx4 v[244:247], v[232:233], off offset:1024
	global_load_dwordx4 v[248:251], v[232:233], off offset:2048
	global_load_dwordx4 v[252:255], v[232:233], off offset:3072
; #define PG8_STAGE(bufoff, gbase, voff) do { _Pragma("unroll") for (int _i = 0; _i < 2; ++_i) \
;         __builtin_amdgcn_global_load_lds((const unsigned*)((const char*)(gbase) + (voff)[_i]), (PG8_LAS unsigned*)(lds + (bufoff) + ldsw + _i * 8192), 16, 0, PG8_LOAD_AUX); } while (0)
; #define PG8_LDA(dst, b, h) do { _Pragma("unroll") for (int m = 0; m < 4; ++m) _Pragma("unroll") for (int k = 0; k < 2; ++k) dst[m][k] = *(const PG8_LAS bf16x8*)(lds + PG8_SA(b, h) + aoff + m * 2048 + k * 1024); } while (0)
; #define PG8_MMA(ai, bj, At, Bt) do { __builtin_amdgcn_s_setprio(1); _Pragma("unroll") for (int m = 0; m < 4; ++m) _Pragma("unroll") for (int n = 0; n < 2; ++n) _Pragma("unroll") for (int k = 0; k < 2; ++k) \
;         acc[ai][bj][m][n] = __builtin_amdgcn_mfma_f32_16x16x32_bf16(Bt[n][k], At[m][k], acc[ai][bj][m][n], 0, 0, 0); __builtin_amdgcn_s_setprio(0); } while (0)
; #define PG8_WAIT_V(n) asm volatile("s_waitcnt vmcnt(" #n ")" ::: "memory")
; #define PG8_WAIT_L(n) asm volatile("s_waitcnt lgkmcnt(" #n ")" ::: "memory")
; #define PG8_BAR __builtin_amdgcn_s_barrier()
; #define PG8_SCHED __builtin_amdgcn_sched_barrier(0)
; __device__ __forceinline__ float rstd_from_slots(const float* slots, int row, int fq) {
;     const f32x4 s4 = *(const f32x4*)(slots + (size_t)row * 16 + 4 * fq);
;     float s = (s4[0] + s4[1]) + (s4[2] + s4[3]);
;     s += __shfl_xor(s, 16); s += __shfl_xor(s, 32);
; template <class Epi, class Sched, bool ALIGN_EPI = false, bool SP2 = false>
; __device__ __forceinline__ void gemm_phase(PG8_LAS unsigned char* lds, const Gemm g, const Sched& S, const Epi& E) {
;     ...
;             PG8_LDA(At, 1, 1); PG8_STAGE(PG8_SB(1, 0), b3, voffB); PG8_STAGE(PG8_SB(1, 1), b3 + hstepB, voffB); PG8_STAGE(PG8_SA(1, 0), a3, voffA);
;             PG8_WAIT_V(8); PG8_WAIT_L(0); PG8_BAR; PG8_MMA(1, 0, At, B0); PG8_MMA(1, 1, At, B1); PG8_BAR; PG8_SCHED;
.Lnoslot_P7:
	s_barrier
	s_waitcnt lgkmcnt(0)
	v_mfma_f32_16x16x32_bf16 v[60:63], v[146:149], v[192:195], v[60:63]
	v_mfma_f32_16x16x32_bf16 v[56:59], v[168:171], v[192:195], v[56:59]
	v_mfma_f32_16x16x32_bf16 v[44:47], v[146:149], v[200:203], v[44:47]
	v_mfma_f32_16x16x32_bf16 v[40:43], v[168:171], v[200:203], v[40:43]
	v_mfma_f32_16x16x32_bf16 v[28:31], v[146:149], v[208:211], v[28:31]
	v_mfma_f32_16x16x32_bf16 v[24:27], v[168:171], v[208:211], v[24:27]
	v_mfma_f32_16x16x32_bf16 v[12:15], v[146:149], v[216:219], v[12:15]
	v_mfma_f32_16x16x32_bf16 v[8:11], v[168:171], v[216:219], v[8:11]
	v_mfma_f32_16x16x32_bf16 v[60:63], v[164:167], v[196:199], v[60:63]
	v_mfma_f32_16x16x32_bf16 v[56:59], v[172:175], v[196:199], v[56:59]
	v_mfma_f32_16x16x32_bf16 v[44:47], v[164:167], v[204:207], v[44:47]
	v_mfma_f32_16x16x32_bf16 v[40:43], v[172:175], v[204:207], v[40:43]
	v_mfma_f32_16x16x32_bf16 v[28:31], v[164:167], v[212:215], v[28:31]
	v_mfma_f32_16x16x32_bf16 v[24:27], v[172:175], v[212:215], v[24:27]
	v_mfma_f32_16x16x32_bf16 v[12:15], v[164:167], v[220:223], v[12:15]
	v_mfma_f32_16x16x32_bf16 v[8:11], v[172:175], v[220:223], v[8:11]
	v_mfma_f32_16x16x32_bf16 v[52:55], v[176:179], v[192:195], v[52:55]
	v_mfma_f32_16x16x32_bf16 v[48:51], v[184:187], v[192:195], v[48:51]
	v_mfma_f32_16x16x32_bf16 v[36:39], v[176:179], v[200:203], v[36:39]
	v_mfma_f32_16x16x32_bf16 v[32:35], v[184:187], v[200:203], v[32:35]
	v_mfma_f32_16x16x32_bf16 v[20:23], v[176:179], v[208:211], v[20:23]
	v_mfma_f32_16x16x32_bf16 v[16:19], v[184:187], v[208:211], v[16:19]
	v_mfma_f32_16x16x32_bf16 v[4:7], v[176:179], v[216:219], v[4:7]
	v_mfma_f32_16x16x32_bf16 v[0:3], v[184:187], v[216:219], v[0:3]
	v_mfma_f32_16x16x32_bf16 v[52:55], v[180:183], v[196:199], v[52:55]
	v_mfma_f32_16x16x32_bf16 v[48:51], v[188:191], v[196:199], v[48:51]
	v_mfma_f32_16x16x32_bf16 v[36:39], v[180:183], v[204:207], v[36:39]
	v_mfma_f32_16x16x32_bf16 v[32:35], v[188:191], v[204:207], v[32:35]
	v_mfma_f32_16x16x32_bf16 v[20:23], v[180:183], v[212:215], v[20:23]
	v_mfma_f32_16x16x32_bf16 v[16:19], v[188:191], v[212:215], v[16:19]
	v_mfma_f32_16x16x32_bf16 v[4:7], v[180:183], v[220:223], v[4:7]
	v_mfma_f32_16x16x32_bf16 v[0:3], v[188:191], v[220:223], v[0:3]
	s_barrier
	s_add_i32 s28, s28, 2
	s_add_u32 s20, s20, 0x100
	s_addc_u32 s21, s21, 0
	s_add_u32 s26, s26, 0x100
	s_addc_u32 s27, s27, 0
	s_cmp_gt_u32 s28, 13
	s_cbranch_scc0 .LBB0_672
	v_add_co_u32_e32 v206, vcc, 0x2000, v232
	s_nop 1
	v_addc_co_u32_e32 v207, vcc, 0, v233, vcc
	global_load_dwordx4 v[188:191], v[206:207], off
	global_load_dwordx4 v[192:195], v[206:207], off offset:1024
	global_load_dwordx4 v[196:199], v[206:207], off offset:2048
	global_load_dwordx4 v[200:203], v[206:207], off offset:3072
	s_and_b64 vcc, exec, s[12:13]
	s_cbranch_vccz .LBB0_675
	s_barrier
.LBB0_675:
	v_xor_b32_e32 v216, 16, v161
	v_xor_b32_e32 v217, 32, v161
	v_lshlrev_b32_e32 v216, 2, v216
	v_lshlrev_b32_e32 v217, 2, v217
	v_lshl_add_u32 v150, s0, 8, v152
	v_lshl_or_b32 v148, s1, 7, v157
	v_mov_b64_e32 v[146:147], s[10:11]
	v_ashrrev_i32_e32 v149, 31, v148
	v_lshlrev_b64 v[148:149], 1, v[148:149]
	s_andn2_b64 vcc, exec, s[2:3]
	v_mad_i64_i32 v[164:165], s[0:1], v150, s56, v[146:147]
	v_lshl_add_u64 v[164:165], v[164:165], 0, v[148:149]
	s_mov_b64 s[0:1], -1
	s_mov_b32 s98, 0x16000
	s_mov_b32 s99, 0
	v_pk_mul_f32 v[112:113], v[120:121], v[112:113]
	v_pk_mul_f32 v[114:115], v[122:123], v[114:115]
	v_pk_mul_f32 v[116:117], v[124:125], v[116:117]
	v_pk_mul_f32 v[118:119], v[126:127], v[118:119]
	v_pk_mul_f32 v[96:97], v[104:105], v[96:97]
	v_pk_mul_f32 v[98:99], v[106:107], v[98:99]
	v_pk_mul_f32 v[100:101], v[108:109], v[100:101]
	v_pk_mul_f32 v[102:103], v[110:111], v[102:103]
	v_pk_mul_f32 v[80:81], v[88:89], v[80:81]
	v_pk_mul_f32 v[82:83], v[90:91], v[82:83]
	v_pk_mul_f32 v[84:85], v[92:93], v[84:85]
	v_pk_mul_f32 v[86:87], v[94:95], v[86:87]
	v_pk_mul_f32 v[64:65], v[72:73], v[64:65]
	v_pk_mul_f32 v[66:67], v[74:75], v[66:67]
	v_pk_mul_f32 v[68:69], v[76:77], v[68:69]
	v_pk_mul_f32 v[70:71], v[78:79], v[70:71]
	v_pk_mul_f32 v[48:49], v[56:57], v[48:49]
	v_pk_mul_f32 v[50:51], v[58:59], v[50:51]
	v_pk_mul_f32 v[52:53], v[60:61], v[52:53]
	v_pk_mul_f32 v[54:55], v[62:63], v[54:55]
	v_pk_mul_f32 v[32:33], v[40:41], v[32:33]
	v_pk_mul_f32 v[34:35], v[42:43], v[34:35]
	v_pk_mul_f32 v[36:37], v[44:45], v[36:37]
	v_pk_mul_f32 v[38:39], v[46:47], v[38:39]
	v_pk_mul_f32 v[16:17], v[24:25], v[16:17]
	v_pk_mul_f32 v[18:19], v[26:27], v[18:19]
	v_pk_mul_f32 v[20:21], v[28:29], v[20:21]
	v_pk_mul_f32 v[22:23], v[30:31], v[22:23]
	v_pk_mul_f32 v[0:1], v[8:9], v[0:1]
	v_pk_mul_f32 v[2:3], v[10:11], v[2:3]
	v_pk_mul_f32 v[4:5], v[12:13], v[4:5]
	v_pk_mul_f32 v[6:7], v[14:15], v[6:7]
	s_waitcnt vmcnt(4)
	v_add_f32_e32 v240, v240, v241
	v_add_f32_e32 v244, v244, v245
	v_add_f32_e32 v248, v248, v249
	v_add_f32_e32 v252, v252, v253
	v_add_f32_e32 v241, v243, v242
	v_add_f32_e32 v245, v247, v246
	v_add_f32_e32 v249, v251, v250
	v_add_f32_e32 v253, v255, v254
	v_add_f32_e32 v240, v240, v241
	v_add_f32_e32 v244, v244, v245
	v_add_f32_e32 v248, v248, v249
	v_add_f32_e32 v252, v252, v253
	ds_bpermute_b32 v241, v216, v240
	ds_bpermute_b32 v245, v216, v244
	ds_bpermute_b32 v249, v216, v248
	ds_bpermute_b32 v253, v216, v252
	s_waitcnt lgkmcnt(0)
	v_add_f32_e32 v240, v240, v241
	v_add_f32_e32 v244, v244, v245
	v_add_f32_e32 v248, v248, v249
	v_add_f32_e32 v252, v252, v253
	ds_bpermute_b32 v241, v217, v240
	ds_bpermute_b32 v245, v217, v244
	ds_bpermute_b32 v249, v217, v248
	ds_bpermute_b32 v253, v217, v252
	s_waitcnt lgkmcnt(0)
; __device__ __forceinline__ unsigned cvt_pk_bf16(float lo, float hi) { const cvt_f32x2_t v = {lo, hi}; const cvt_bf16x2_t b = __builtin_convertvector(v, cvt_bf16x2_t); return __builtin_bit_cast(unsigned, b); }
; __device__ __forceinline__ float rstd_from_slots(const float* slots, int row, int fq) {
;     const f32x4 s4 = *(const f32x4*)(slots + (size_t)row * 16 + 4 * fq);
;     float s = (s4[0] + s4[1]) + (s4[2] + s4[3]);
;     s += __shfl_xor(s, 16); s += __shfl_xor(s, 32);
;     return __builtin_amdgcn_rsqf(s * (1.0f / 1024.0f) + RMS_EPS_F);
; __device__ __forceinline__ float silu_mul(float g, float u) { return g * u * __builtin_amdgcn_rcpf(1.0f + __builtin_amdgcn_exp2f(g * -1.4426950408889634f)); }
;     __device__ __forceinline__ void operator()(const f32x4 (&acc)[2][2][4][2], const Unit& u, int wr, int wc, int fr, int fq) const {
;         const int row0 = u.pm * BM + wr * 64 + fr; const int col0 = u.pn * HALF + wc * 32 + 8 * fq;
; #pragma unroll
;         for (int ai = 0; ai < 2; ++ai)
; #pragma unroll
;             for (int m = 0; m < 4; ++m) { const int row = row0 + ai * HALF + m * 16;
;                 const float sc = rstd_from_slots(slots, row, fq);
;                 const f32x4 g0 = acc[ai][0][m][0] * sc, g1 = acc[ai][0][m][1] * sc, u0 = acc[ai][1][m][0] * sc, u1 = acc[ai][1][m][1] * sc;
;                 u32x4 w; w.x = cvt_pk_bf16(silu_mul(g0[0], u0[0]), silu_mul(g0[1], u0[1])); w.y = cvt_pk_bf16(silu_mul(g0[2], u0[2]), silu_mul(g0[3], u0[3]));
;                 w.z = cvt_pk_bf16(silu_mul(g1[0], u1[0]), silu_mul(g1[1], u1[1])); w.w = cvt_pk_bf16(silu_mul(g1[2], u1[2]), silu_mul(g1[3], u1[3]));
;                 __builtin_nontemporal_store(w, (u32x4*)(O + (size_t)row * ldc + col0)); }
	v_add_f32_e32 v240, v240, v241
	v_add_f32_e32 v244, v244, v245
	v_add_f32_e32 v248, v248, v249
	v_add_f32_e32 v252, v252, v253
	v_fmamk_f32 v241, v240, 0x3a800000, v162
	v_fmamk_f32 v245, v244, 0x3a800000, v162
	v_fmamk_f32 v249, v248, 0x3a800000, v162
	v_fmamk_f32 v253, v252, 0x3a800000, v162
	v_rsq_f32_e32 v240, v241
	v_rsq_f32_e32 v244, v245
	v_rsq_f32_e32 v248, v249
	v_rsq_f32_e32 v252, v253
	s_nop 0
	v_mul_f32_e32 v240, 0xbfb8aa3b, v240
	v_mul_f32_e32 v244, 0xbfb8aa3b, v244
	v_mul_f32_e32 v248, 0xbfb8aa3b, v248
	v_mul_f32_e32 v252, 0xbfb8aa3b, v252
	v_mul_f32_e32 v120, v240, v120
	v_mul_f32_e32 v121, v240, v121
	v_mul_f32_e32 v122, v240, v122
	v_mul_f32_e32 v123, v240, v123
	v_mul_f32_e32 v124, v240, v124
	v_mul_f32_e32 v125, v240, v125
	v_mul_f32_e32 v126, v240, v126
	v_mul_f32_e32 v127, v240, v127
	v_exp_f32_e32 v120, v120
	v_exp_f32_e32 v121, v121
	v_exp_f32_e32 v122, v122
	v_exp_f32_e32 v123, v123
	v_exp_f32_e32 v124, v124
	v_exp_f32_e32 v125, v125
	v_exp_f32_e32 v126, v126
	v_exp_f32_e32 v127, v127
	v_fma_f32 v120, v120, v241, v241
	v_fma_f32 v121, v121, v241, v241
	v_fma_f32 v122, v122, v241, v241
	v_fma_f32 v123, v123, v241, v241
	v_fma_f32 v124, v124, v241, v241
	v_fma_f32 v125, v125, v241, v241
	v_fma_f32 v126, v126, v241, v241
	v_fma_f32 v127, v127, v241, v241
	v_rcp_f32_e32 v120, v120
	v_rcp_f32_e32 v121, v121
	v_rcp_f32_e32 v122, v122
	v_rcp_f32_e32 v123, v123
	v_rcp_f32_e32 v124, v124
	v_rcp_f32_e32 v125, v125
	v_rcp_f32_e32 v126, v126
	v_rcp_f32_e32 v127, v127
	v_pk_mul_f32 v[112:113], v[112:113], v[120:121]
	v_pk_mul_f32 v[114:115], v[114:115], v[122:123]
	v_pk_mul_f32 v[116:117], v[116:117], v[124:125]
	v_pk_mul_f32 v[118:119], v[118:119], v[126:127]
	v_cvt_pk_bf16_f32 v120, v116, v117
	v_cvt_pk_bf16_f32 v121, v118, v119
	v_cvt_pk_bf16_f32 v122, v112, v113
	v_cvt_pk_bf16_f32 v123, v114, v115
	global_store_dwordx4 v[164:165], v[120:123], off nt
	v_lshl_add_u64 v[166:167], v[164:165], 0, s[98:99]
	v_mul_f32_e32 v104, v244, v104
	v_mul_f32_e32 v105, v244, v105
	v_mul_f32_e32 v106, v244, v106
	v_mul_f32_e32 v107, v244, v107
	v_mul_f32_e32 v108, v244, v108
	v_mul_f32_e32 v109, v244, v109
	v_mul_f32_e32 v110, v244, v110
	v_mul_f32_e32 v111, v244, v111
	v_exp_f32_e32 v104, v104
	v_exp_f32_e32 v105, v105
	v_exp_f32_e32 v106, v106
	v_exp_f32_e32 v107, v107
	v_exp_f32_e32 v108, v108
	v_exp_f32_e32 v109, v109
	v_exp_f32_e32 v110, v110
	v_exp_f32_e32 v111, v111
	v_fma_f32 v104, v104, v245, v245
	v_fma_f32 v105, v105, v245, v245
	v_fma_f32 v106, v106, v245, v245
	v_fma_f32 v107, v107, v245, v245
	v_fma_f32 v108, v108, v245, v245
	v_fma_f32 v109, v109, v245, v245
	v_fma_f32 v110, v110, v245, v245
	v_fma_f32 v111, v111, v245, v245
	v_rcp_f32_e32 v104, v104
	v_rcp_f32_e32 v105, v105
	v_rcp_f32_e32 v106, v106
	v_rcp_f32_e32 v107, v107
	v_rcp_f32_e32 v108, v108
	v_rcp_f32_e32 v109, v109
	v_rcp_f32_e32 v110, v110
	v_rcp_f32_e32 v111, v111
	v_pk_mul_f32 v[96:97], v[96:97], v[104:105]
	v_pk_mul_f32 v[98:99], v[98:99], v[106:107]
	v_pk_mul_f32 v[100:101], v[100:101], v[108:109]
	v_pk_mul_f32 v[102:103], v[102:103], v[110:111]
	v_cvt_pk_bf16_f32 v104, v100, v101
	v_cvt_pk_bf16_f32 v105, v102, v103
	v_cvt_pk_bf16_f32 v106, v96, v97
	v_cvt_pk_bf16_f32 v107, v98, v99
	global_store_dwordx4 v[166:167], v[104:107], off nt
	v_lshl_add_u64 v[164:165], v[166:167], 0, s[98:99]
	v_mul_f32_e32 v88, v248, v88
	v_mul_f32_e32 v89, v248, v89
	v_mul_f32_e32 v90, v248, v90
	v_mul_f32_e32 v91, v248, v91
	v_mul_f32_e32 v92, v248, v92
	v_mul_f32_e32 v93, v248, v93
	v_mul_f32_e32 v94, v248, v94
	v_mul_f32_e32 v95, v248, v95
	v_exp_f32_e32 v88, v88
	v_exp_f32_e32 v89, v89
	v_exp_f32_e32 v90, v90
	v_exp_f32_e32 v91, v91
	v_exp_f32_e32 v92, v92
	v_exp_f32_e32 v93, v93
	v_exp_f32_e32 v94, v94
	v_exp_f32_e32 v95, v95
	v_fma_f32 v88, v88, v249, v249
	v_fma_f32 v89, v89, v249, v249
	v_fma_f32 v90, v90, v249, v249
	v_fma_f32 v91, v91, v249, v249
	v_fma_f32 v92, v92, v249, v249
	v_fma_f32 v93, v93, v249, v249
	v_fma_f32 v94, v94, v249, v249
	v_fma_f32 v95, v95, v249, v249
	v_rcp_f32_e32 v88, v88
	v_rcp_f32_e32 v89, v89
	v_rcp_f32_e32 v90, v90
	v_rcp_f32_e32 v91, v91
	v_rcp_f32_e32 v92, v92
	v_rcp_f32_e32 v93, v93
	v_rcp_f32_e32 v94, v94
	v_rcp_f32_e32 v95, v95
	v_pk_mul_f32 v[80:81], v[80:81], v[88:89]
	v_pk_mul_f32 v[82:83], v[82:83], v[90:91]
	v_pk_mul_f32 v[84:85], v[84:85], v[92:93]
	v_pk_mul_f32 v[86:87], v[86:87], v[94:95]
	v_cvt_pk_bf16_f32 v88, v84, v85
	v_cvt_pk_bf16_f32 v89, v86, v87
	v_cvt_pk_bf16_f32 v90, v80, v81
	v_cvt_pk_bf16_f32 v91, v82, v83
	global_store_dwordx4 v[164:165], v[88:91], off nt
	v_lshl_add_u64 v[166:167], v[164:165], 0, s[98:99]
	v_mul_f32_e32 v72, v252, v72
	v_mul_f32_e32 v73, v252, v73
	v_mul_f32_e32 v74, v252, v74
	v_mul_f32_e32 v75, v252, v75
	v_mul_f32_e32 v76, v252, v76
	v_mul_f32_e32 v77, v252, v77
	v_mul_f32_e32 v78, v252, v78
	v_mul_f32_e32 v79, v252, v79
	v_exp_f32_e32 v72, v72
	v_exp_f32_e32 v73, v73
	v_exp_f32_e32 v74, v74
	v_exp_f32_e32 v75, v75
	v_exp_f32_e32 v76, v76
	v_exp_f32_e32 v77, v77
	v_exp_f32_e32 v78, v78
	v_exp_f32_e32 v79, v79
	v_fma_f32 v72, v72, v253, v253
	v_fma_f32 v73, v73, v253, v253
	v_fma_f32 v74, v74, v253, v253
	v_fma_f32 v75, v75, v253, v253
	v_fma_f32 v76, v76, v253, v253
	v_fma_f32 v77, v77, v253, v253
	v_fma_f32 v78, v78, v253, v253
	v_fma_f32 v79, v79, v253, v253
	v_rcp_f32_e32 v72, v72
	v_rcp_f32_e32 v73, v73
	v_rcp_f32_e32 v74, v74
	v_rcp_f32_e32 v75, v75
	v_rcp_f32_e32 v76, v76
	v_rcp_f32_e32 v77, v77
	v_rcp_f32_e32 v78, v78
	v_rcp_f32_e32 v79, v79
	v_pk_mul_f32 v[64:65], v[64:65], v[72:73]
	v_pk_mul_f32 v[66:67], v[66:67], v[74:75]
	v_pk_mul_f32 v[68:69], v[68:69], v[76:77]
	v_pk_mul_f32 v[70:71], v[70:71], v[78:79]
	v_cvt_pk_bf16_f32 v72, v68, v69
	v_cvt_pk_bf16_f32 v73, v70, v71
	v_cvt_pk_bf16_f32 v74, v64, v65
	v_cvt_pk_bf16_f32 v75, v66, v67
	global_store_dwordx4 v[166:167], v[72:75], off nt
	s_waitcnt vmcnt(4)
; __device__ __forceinline__ unsigned cvt_pk_bf16(float lo, float hi) { const cvt_f32x2_t v = {lo, hi}; const cvt_bf16x2_t b = __builtin_convertvector(v, cvt_bf16x2_t); return __builtin_bit_cast(unsigned, b); }
; __device__ __forceinline__ float rstd_from_slots(const float* slots, int row, int fq) {
;     const f32x4 s4 = *(const f32x4*)(slots + (size_t)row * 16 + 4 * fq);
;     float s = (s4[0] + s4[1]) + (s4[2] + s4[3]);
;     s += __shfl_xor(s, 16); s += __shfl_xor(s, 32);
;     return __builtin_amdgcn_rsqf(s * (1.0f / 1024.0f) + RMS_EPS_F);
; __device__ __forceinline__ float silu_mul(float g, float u) { return g * u * __builtin_amdgcn_rcpf(1.0f + __builtin_amdgcn_exp2f(g * -1.4426950408889634f)); }
;     __device__ __forceinline__ void operator()(const f32x4 (&acc)[2][2][4][2], const Unit& u, int wr, int wc, int fr, int fq) const {
;         const int row0 = u.pm * BM + wr * 64 + fr; const int col0 = u.pn * HALF + wc * 32 + 8 * fq;
; #pragma unroll
;         for (int ai = 0; ai < 2; ++ai)
; #pragma unroll
;             for (int m = 0; m < 4; ++m) { const int row = row0 + ai * HALF + m * 16;
;                 const float sc = rstd_from_slots(slots, row, fq);
;                 const f32x4 g0 = acc[ai][0][m][0] * sc, g1 = acc[ai][0][m][1] * sc, u0 = acc[ai][1][m][0] * sc, u1 = acc[ai][1][m][1] * sc;
;                 u32x4 w; w.x = cvt_pk_bf16(silu_mul(g0[0], u0[0]), silu_mul(g0[1], u0[1])); w.y = cvt_pk_bf16(silu_mul(g0[2], u0[2]), silu_mul(g0[3], u0[3]));
;                 w.z = cvt_pk_bf16(silu_mul(g1[0], u1[0]), silu_mul(g1[1], u1[1])); w.w = cvt_pk_bf16(silu_mul(g1[2], u1[2]), silu_mul(g1[3], u1[3]));
;                 __builtin_nontemporal_store(w, (u32x4*)(O + (size_t)row * ldc + col0)); }
	v_add_f32_e32 v188, v188, v189
	v_add_f32_e32 v192, v192, v193
	v_add_f32_e32 v196, v196, v197
	v_add_f32_e32 v200, v200, v201
	v_add_f32_e32 v189, v191, v190
	v_add_f32_e32 v193, v195, v194
	v_add_f32_e32 v197, v199, v198
	v_add_f32_e32 v201, v203, v202
	v_add_f32_e32 v188, v188, v189
	v_add_f32_e32 v192, v192, v193
	v_add_f32_e32 v196, v196, v197
	v_add_f32_e32 v200, v200, v201
	ds_bpermute_b32 v189, v216, v188
	ds_bpermute_b32 v193, v216, v192
	ds_bpermute_b32 v197, v216, v196
	ds_bpermute_b32 v201, v216, v200
	s_waitcnt lgkmcnt(0)
	v_add_f32_e32 v188, v188, v189
	v_add_f32_e32 v192, v192, v193
	v_add_f32_e32 v196, v196, v197
	v_add_f32_e32 v200, v200, v201
	ds_bpermute_b32 v189, v217, v188
	ds_bpermute_b32 v193, v217, v192
	ds_bpermute_b32 v197, v217, v196
	ds_bpermute_b32 v201, v217, v200
	s_waitcnt lgkmcnt(0)
	v_add_f32_e32 v188, v188, v189
	v_add_f32_e32 v192, v192, v193
	v_add_f32_e32 v196, v196, v197
	v_add_f32_e32 v200, v200, v201
	v_fmamk_f32 v189, v188, 0x3a800000, v162
	v_fmamk_f32 v193, v192, 0x3a800000, v162
	v_fmamk_f32 v197, v196, 0x3a800000, v162
	v_fmamk_f32 v201, v200, 0x3a800000, v162
	v_rsq_f32_e32 v188, v189
	v_rsq_f32_e32 v192, v193
	v_rsq_f32_e32 v196, v197
	v_rsq_f32_e32 v200, v201
	s_nop 0
	v_mul_f32_e32 v188, 0xbfb8aa3b, v188
	v_mul_f32_e32 v192, 0xbfb8aa3b, v192
	v_mul_f32_e32 v196, 0xbfb8aa3b, v196
	v_mul_f32_e32 v200, 0xbfb8aa3b, v200
	s_mov_b32 s98, 0x6e000
	v_lshl_add_u64 v[164:165], v[166:167], 0, s[98:99]
	s_mov_b32 s98, 0x16000
	v_mul_f32_e32 v56, v188, v56
	v_mul_f32_e32 v57, v188, v57
	v_mul_f32_e32 v58, v188, v58
	v_mul_f32_e32 v59, v188, v59
	v_mul_f32_e32 v60, v188, v60
	v_mul_f32_e32 v61, v188, v61
	v_mul_f32_e32 v62, v188, v62
	v_mul_f32_e32 v63, v188, v63
	v_exp_f32_e32 v56, v56
	v_exp_f32_e32 v57, v57
	v_exp_f32_e32 v58, v58
	v_exp_f32_e32 v59, v59
	v_exp_f32_e32 v60, v60
	v_exp_f32_e32 v61, v61
	v_exp_f32_e32 v62, v62
	v_exp_f32_e32 v63, v63
	v_fma_f32 v56, v56, v189, v189
	v_fma_f32 v57, v57, v189, v189
	v_fma_f32 v58, v58, v189, v189
	v_fma_f32 v59, v59, v189, v189
	v_fma_f32 v60, v60, v189, v189
	v_fma_f32 v61, v61, v189, v189
	v_fma_f32 v62, v62, v189, v189
	v_fma_f32 v63, v63, v189, v189
	v_rcp_f32_e32 v56, v56
	v_rcp_f32_e32 v57, v57
	v_rcp_f32_e32 v58, v58
	v_rcp_f32_e32 v59, v59
	v_rcp_f32_e32 v60, v60
	v_rcp_f32_e32 v61, v61
	v_rcp_f32_e32 v62, v62
	v_rcp_f32_e32 v63, v63
	v_pk_mul_f32 v[48:49], v[48:49], v[56:57]
	v_pk_mul_f32 v[50:51], v[50:51], v[58:59]
	v_pk_mul_f32 v[52:53], v[52:53], v[60:61]
	v_pk_mul_f32 v[54:55], v[54:55], v[62:63]
	v_cvt_pk_bf16_f32 v56, v52, v53
	v_cvt_pk_bf16_f32 v57, v54, v55
	v_cvt_pk_bf16_f32 v58, v48, v49
	v_cvt_pk_bf16_f32 v59, v50, v51
	global_store_dwordx4 v[164:165], v[56:59], off nt
	v_lshl_add_u64 v[166:167], v[164:165], 0, s[98:99]
	v_mul_f32_e32 v40, v192, v40
	v_mul_f32_e32 v41, v192, v41
	v_mul_f32_e32 v42, v192, v42
	v_mul_f32_e32 v43, v192, v43
	v_mul_f32_e32 v44, v192, v44
	v_mul_f32_e32 v45, v192, v45
	v_mul_f32_e32 v46, v192, v46
	v_mul_f32_e32 v47, v192, v47
	v_exp_f32_e32 v40, v40
	v_exp_f32_e32 v41, v41
	v_exp_f32_e32 v42, v42
	v_exp_f32_e32 v43, v43
	v_exp_f32_e32 v44, v44
	v_exp_f32_e32 v45, v45
	v_exp_f32_e32 v46, v46
	v_exp_f32_e32 v47, v47
	v_fma_f32 v40, v40, v193, v193
	v_fma_f32 v41, v41, v193, v193
	v_fma_f32 v42, v42, v193, v193
	v_fma_f32 v43, v43, v193, v193
	v_fma_f32 v44, v44, v193, v193
	v_fma_f32 v45, v45, v193, v193
	v_fma_f32 v46, v46, v193, v193
	v_fma_f32 v47, v47, v193, v193
	v_rcp_f32_e32 v40, v40
	v_rcp_f32_e32 v41, v41
	v_rcp_f32_e32 v42, v42
	v_rcp_f32_e32 v43, v43
	v_rcp_f32_e32 v44, v44
	v_rcp_f32_e32 v45, v45
	v_rcp_f32_e32 v46, v46
	v_rcp_f32_e32 v47, v47
	v_pk_mul_f32 v[32:33], v[32:33], v[40:41]
	v_pk_mul_f32 v[34:35], v[34:35], v[42:43]
	v_pk_mul_f32 v[36:37], v[36:37], v[44:45]
	v_pk_mul_f32 v[38:39], v[38:39], v[46:47]
	v_cvt_pk_bf16_f32 v40, v36, v37
	v_cvt_pk_bf16_f32 v41, v38, v39
	v_cvt_pk_bf16_f32 v42, v32, v33
	v_cvt_pk_bf16_f32 v43, v34, v35
	global_store_dwordx4 v[166:167], v[40:43], off nt
	v_lshl_add_u64 v[164:165], v[166:167], 0, s[98:99]
	v_mul_f32_e32 v24, v196, v24
	v_mul_f32_e32 v25, v196, v25
	v_mul_f32_e32 v26, v196, v26
	v_mul_f32_e32 v27, v196, v27
	v_mul_f32_e32 v28, v196, v28
	v_mul_f32_e32 v29, v196, v29
	v_mul_f32_e32 v30, v196, v30
	v_mul_f32_e32 v31, v196, v31
	v_exp_f32_e32 v24, v24
	v_exp_f32_e32 v25, v25
	v_exp_f32_e32 v26, v26
	v_exp_f32_e32 v27, v27
	v_exp_f32_e32 v28, v28
	v_exp_f32_e32 v29, v29
	v_exp_f32_e32 v30, v30
	v_exp_f32_e32 v31, v31
	v_fma_f32 v24, v24, v197, v197
	v_fma_f32 v25, v25, v197, v197
	v_fma_f32 v26, v26, v197, v197
	v_fma_f32 v27, v27, v197, v197
	v_fma_f32 v28, v28, v197, v197
	v_fma_f32 v29, v29, v197, v197
	v_fma_f32 v30, v30, v197, v197
	v_fma_f32 v31, v31, v197, v197
	v_rcp_f32_e32 v24, v24
	v_rcp_f32_e32 v25, v25
	v_rcp_f32_e32 v26, v26
	v_rcp_f32_e32 v27, v27
	v_rcp_f32_e32 v28, v28
	v_rcp_f32_e32 v29, v29
	v_rcp_f32_e32 v30, v30
	v_rcp_f32_e32 v31, v31
	v_pk_mul_f32 v[16:17], v[16:17], v[24:25]
	v_pk_mul_f32 v[18:19], v[18:19], v[26:27]
	v_pk_mul_f32 v[20:21], v[20:21], v[28:29]
	v_pk_mul_f32 v[22:23], v[22:23], v[30:31]
	v_cvt_pk_bf16_f32 v24, v20, v21
	v_cvt_pk_bf16_f32 v25, v22, v23
	v_cvt_pk_bf16_f32 v26, v16, v17
	v_cvt_pk_bf16_f32 v27, v18, v19
	global_store_dwordx4 v[164:165], v[24:27], off nt
	v_lshl_add_u64 v[166:167], v[164:165], 0, s[98:99]
	v_mul_f32_e32 v8, v200, v8
	v_mul_f32_e32 v9, v200, v9
	v_mul_f32_e32 v10, v200, v10
	v_mul_f32_e32 v11, v200, v11
	v_mul_f32_e32 v12, v200, v12
	v_mul_f32_e32 v13, v200, v13
	v_mul_f32_e32 v14, v200, v14
	v_mul_f32_e32 v15, v200, v15
	v_exp_f32_e32 v8, v8
	v_exp_f32_e32 v9, v9
	v_exp_f32_e32 v10, v10
	v_exp_f32_e32 v11, v11
	v_exp_f32_e32 v12, v12
	v_exp_f32_e32 v13, v13
	v_exp_f32_e32 v14, v14
	v_exp_f32_e32 v15, v15
	v_fma_f32 v8, v8, v201, v201
	v_fma_f32 v9, v9, v201, v201
	v_fma_f32 v10, v10, v201, v201
	v_fma_f32 v11, v11, v201, v201
	v_fma_f32 v12, v12, v201, v201
	v_fma_f32 v13, v13, v201, v201
	v_fma_f32 v14, v14, v201, v201
	v_fma_f32 v15, v15, v201, v201
	v_rcp_f32_e32 v8, v8
	v_rcp_f32_e32 v9, v9
	v_rcp_f32_e32 v10, v10
	v_rcp_f32_e32 v11, v11
	v_rcp_f32_e32 v12, v12
	v_rcp_f32_e32 v13, v13
	v_rcp_f32_e32 v14, v14
	v_rcp_f32_e32 v15, v15
	v_pk_mul_f32 v[0:1], v[0:1], v[8:9]
	v_pk_mul_f32 v[2:3], v[2:3], v[10:11]
	v_pk_mul_f32 v[4:5], v[4:5], v[12:13]
	v_pk_mul_f32 v[6:7], v[6:7], v[14:15]
	v_cvt_pk_bf16_f32 v8, v4, v5
	v_cvt_pk_bf16_f32 v9, v6, v7
	v_cvt_pk_bf16_f32 v10, v0, v1
	v_cvt_pk_bf16_f32 v11, v2, v3
	global_store_dwordx4 v[166:167], v[8:11], off nt
	s_cbranch_vccnz .LBB0_668
	s_andn2_b64 vcc, exec, s[6:7]
	s_cbranch_vccnz .LBB0_667
	s_barrier
	s_branch .LBB0_667

; #define PG8_STAGE(bufoff, gbase, voff) do { _Pragma("unroll") for (int _i = 0; _i < 2; ++_i) \
;         __builtin_amdgcn_global_load_lds((const unsigned*)((const char*)(gbase) + (voff)[_i]), (PG8_LAS unsigned*)(lds + (bufoff) + ldsw + _i * 8192), 16, 0, PG8_LOAD_AUX); } while (0)
; #define PG8_LDA(dst, b, h) do { _Pragma("unroll") for (int m = 0; m < 4; ++m) _Pragma("unroll") for (int k = 0; k < 2; ++k) dst[m][k] = *(const PG8_LAS bf16x8*)(lds + PG8_SA(b, h) + aoff + m * 2048 + k * 1024); } while (0)
; #define PG8_LDB(dst, b, h) do { _Pragma("unroll") for (int n = 0; n < 2; ++n) _Pragma("unroll") for (int k = 0; k < 2; ++k) dst[n][k] = *(const PG8_LAS bf16x8*)(lds + PG8_SB(b, h) + boff + n * 2048 + k * 1024); } while (0)
; #define PG8_MMA(ai, bj, At, Bt) do { __builtin_amdgcn_s_setprio(1); _Pragma("unroll") for (int m = 0; m < 4; ++m) _Pragma("unroll") for (int n = 0; n < 2; ++n) _Pragma("unroll") for (int k = 0; k < 2; ++k) \
;         acc[ai][bj][m][n] = __builtin_amdgcn_mfma_f32_16x16x32_bf16(Bt[n][k], At[m][k], acc[ai][bj][m][n], 0, 0, 0); __builtin_amdgcn_s_setprio(0); } while (0)
; #define PG8_WAIT_V(n) asm volatile("s_waitcnt vmcnt(" #n ")" ::: "memory")
; #define PG8_WAIT_L(n) asm volatile("s_waitcnt lgkmcnt(" #n ")" ::: "memory")
; #define PG8_BAR __builtin_amdgcn_s_barrier()
; #define PG8_SCHED __builtin_amdgcn_sched_barrier(0)
; __device__ __forceinline__ float rstd_from_slots(const float* slots, int row, int fq) {
;     const f32x4 s4 = *(const f32x4*)(slots + (size_t)row * 16 + 4 * fq);
; template <class Epi, class Sched, bool ALIGN_EPI = false, bool SP2 = false>
; __device__ __forceinline__ void gemm_phase(PG8_LAS unsigned char* lds, const Gemm g, const Sched& S, const Epi& E) {
;     ...
;             PG8_LDB(B0, 1, 0); PG8_LDB(B1, 1, 1); PG8_SCHED; PG8_LDA(At, 1, 0); PG8_STAGE(PG8_SA(0, 1), a2 + hstepA, voffA);
;             PG8_WAIT_V(8); PG8_WAIT_L(0); PG8_BAR; PG8_MMA(0, 0, At, B0); PG8_MMA(0, 1, At, B1); PG8_BAR; PG8_SCHED;
;             PG8_LDA(At, 1, 1); PG8_STAGE(PG8_SB(1, 0), b3, voffB); PG8_STAGE(PG8_SB(1, 1), b3 + hstepB, voffB); PG8_STAGE(PG8_SA(1, 0), a3, voffA);
;             PG8_WAIT_V(8); PG8_WAIT_L(0); PG8_BAR; PG8_MMA(1, 0, At, B0); PG8_MMA(1, 1, At, B1); PG8_BAR; PG8_SCHED;
.Lkmid_P12:
	s_add_i32 s29, 0, 0x18000
	s_add_i32 s33, 0, 0x1c000
	v_add_u32_e32 v170, s29, v155
	v_add_u32_e32 v186, s33, v155
	ds_read_b128 v[146:149], v170
	ds_read_b128 v[162:165], v170 offset:1024
	ds_read_b128 v[166:169], v170 offset:2048
	ds_read_b128 v[170:173], v170 offset:3072
	ds_read_b128 v[174:177], v186
	ds_read_b128 v[178:181], v186 offset:1024
	ds_read_b128 v[182:185], v186 offset:2048
	ds_read_b128 v[186:189], v186 offset:3072
	s_add_u32 s30, s34, 0x40000
	s_addc_u32 s31, s35, 0
	s_mov_b32 m0, s47
	v_lshl_add_u64 v[228:229], s[30:31], 0, v[134:135]
	ds_read_b128 v[190:193], v159 offset:32768
	ds_read_b128 v[194:197], v159 offset:33792
	ds_read_b128 v[198:201], v159 offset:34816
	ds_read_b128 v[202:205], v159 offset:35840
	ds_read_b128 v[206:209], v159 offset:36864
	ds_read_b128 v[210:213], v159 offset:37888
	ds_read_b128 v[214:217], v159 offset:38912
	ds_read_b128 v[218:221], v159 offset:39936
	global_load_lds_dwordx4 v[228:229], off
	v_lshl_add_u64 v[228:229], s[30:31], 0, v[130:131]
	s_mov_b32 m0, s48
	s_nop 0
	global_load_lds_dwordx4 v[228:229], off
	s_waitcnt vmcnt(8)
	s_waitcnt lgkmcnt(0)
	s_barrier
	s_waitcnt lgkmcnt(0)
	v_mfma_f32_16x16x32_bf16 v[124:127], v[146:149], v[190:193], v[124:127]
	v_mfma_f32_16x16x32_bf16 v[120:123], v[166:169], v[190:193], v[120:123]
	v_mfma_f32_16x16x32_bf16 v[108:111], v[146:149], v[198:201], v[108:111]
	v_mfma_f32_16x16x32_bf16 v[104:107], v[166:169], v[198:201], v[104:107]
	v_mfma_f32_16x16x32_bf16 v[92:95], v[146:149], v[206:209], v[92:95]
	v_mfma_f32_16x16x32_bf16 v[88:91], v[166:169], v[206:209], v[88:91]
	v_mfma_f32_16x16x32_bf16 v[76:79], v[146:149], v[214:217], v[76:79]
	v_mfma_f32_16x16x32_bf16 v[72:75], v[166:169], v[214:217], v[72:75]
	v_mfma_f32_16x16x32_bf16 v[124:127], v[162:165], v[194:197], v[124:127]
	v_mfma_f32_16x16x32_bf16 v[120:123], v[170:173], v[194:197], v[120:123]
	v_mfma_f32_16x16x32_bf16 v[108:111], v[162:165], v[202:205], v[108:111]
	v_mfma_f32_16x16x32_bf16 v[104:107], v[170:173], v[202:205], v[104:107]
	v_mfma_f32_16x16x32_bf16 v[92:95], v[162:165], v[210:213], v[92:95]
	v_mfma_f32_16x16x32_bf16 v[88:91], v[170:173], v[210:213], v[88:91]
	v_mfma_f32_16x16x32_bf16 v[76:79], v[162:165], v[218:221], v[76:79]
	v_mfma_f32_16x16x32_bf16 v[72:75], v[170:173], v[218:221], v[72:75]
	v_mfma_f32_16x16x32_bf16 v[116:119], v[174:177], v[190:193], v[116:119]
	v_mfma_f32_16x16x32_bf16 v[112:115], v[182:185], v[190:193], v[112:115]
	v_mfma_f32_16x16x32_bf16 v[100:103], v[174:177], v[198:201], v[100:103]
	v_mfma_f32_16x16x32_bf16 v[96:99], v[182:185], v[198:201], v[96:99]
	v_mfma_f32_16x16x32_bf16 v[84:87], v[174:177], v[206:209], v[84:87]
	v_mfma_f32_16x16x32_bf16 v[80:83], v[182:185], v[206:209], v[80:83]
	v_mfma_f32_16x16x32_bf16 v[68:71], v[174:177], v[214:217], v[68:71]
	v_mfma_f32_16x16x32_bf16 v[64:67], v[182:185], v[214:217], v[64:67]
	v_mfma_f32_16x16x32_bf16 v[116:119], v[178:181], v[194:197], v[116:119]
	v_mfma_f32_16x16x32_bf16 v[112:115], v[186:189], v[194:197], v[112:115]
	v_mfma_f32_16x16x32_bf16 v[100:103], v[178:181], v[202:205], v[100:103]
	v_mfma_f32_16x16x32_bf16 v[96:99], v[186:189], v[202:205], v[96:99]
	v_mfma_f32_16x16x32_bf16 v[84:87], v[178:181], v[210:213], v[84:87]
	v_mfma_f32_16x16x32_bf16 v[80:83], v[186:189], v[210:213], v[80:83]
	v_mfma_f32_16x16x32_bf16 v[68:71], v[178:181], v[218:221], v[68:71]
	v_mfma_f32_16x16x32_bf16 v[64:67], v[186:189], v[218:221], v[64:67]
	s_barrier
	s_add_i32 s29, s29, s42
	v_lshl_add_u64 v[150:151], v[150:151], 0, s[8:9]
	s_mov_b32 m0, s29
	ds_read_b128 v[190:193], v159 offset:49152
	ds_read_b128 v[194:197], v159 offset:50176
	ds_read_b128 v[198:201], v159 offset:51200
	ds_read_b128 v[202:205], v159 offset:52224
	ds_read_b128 v[206:209], v159 offset:53248
	ds_read_b128 v[210:213], v159 offset:54272
	ds_read_b128 v[214:217], v159 offset:55296
	ds_read_b128 v[218:221], v159 offset:56320
	global_load_lds_dwordx4 v[150:151], off
	s_add_i32 m0, s29, 0x2000
	s_add_u32 s22, s22, 0x40080
	v_lshl_add_u64 v[150:151], v[222:223], 0, s[8:9]
	s_addc_u32 s23, s23, 0
	s_add_i32 s29, s33, s42
	global_load_lds_dwordx4 v[150:151], off
	v_lshl_add_u64 v[150:151], s[22:23], 0, v[132:133]
	s_mov_b32 m0, s29
	s_nop 0
	global_load_lds_dwordx4 v[150:151], off
	v_lshl_add_u64 v[150:151], s[22:23], 0, v[128:129]
	s_add_i32 m0, s29, 0x2000
	s_nop 0
	global_load_lds_dwordx4 v[150:151], off
	v_lshl_add_u64 v[150:151], v[224:225], 0, s[8:9]
	s_mov_b32 m0, s50
	s_nop 0
	global_load_lds_dwordx4 v[150:151], off
	v_lshl_add_u64 v[150:151], v[226:227], 0, s[8:9]
	s_mov_b32 m0, s51
	s_nop 0
	global_load_lds_dwordx4 v[150:151], off
	s_waitcnt vmcnt(8)
	s_waitcnt lgkmcnt(0)
	s_cmp_lt_i32 s28, 12
	s_cbranch_scc1 .Lnoslot_P12
	v_lshl_add_u32 v232, s0, 8, v152
	v_ashrrev_i32_e32 v233, 31, v232
	v_lshlrev_b64 v[232:233], 6, v[232:233]
	v_lshl_add_u64 v[232:233], v[136:137], 0, v[232:233]
	global_load_dwordx4 v[240:243], v[232:233], off
	global_load_dwordx4 v[244:247], v[232:233], off offset:1024
	global_load_dwordx4 v[248:251], v[232:233], off offset:2048
	global_load_dwordx4 v[252:255], v[232:233], off offset:3072
; #define PG8_STAGE(bufoff, gbase, voff) do { _Pragma("unroll") for (int _i = 0; _i < 2; ++_i) \
;         __builtin_amdgcn_global_load_lds((const unsigned*)((const char*)(gbase) + (voff)[_i]), (PG8_LAS unsigned*)(lds + (bufoff) + ldsw + _i * 8192), 16, 0, PG8_LOAD_AUX); } while (0)
; #define PG8_LDA(dst, b, h) do { _Pragma("unroll") for (int m = 0; m < 4; ++m) _Pragma("unroll") for (int k = 0; k < 2; ++k) dst[m][k] = *(const PG8_LAS bf16x8*)(lds + PG8_SA(b, h) + aoff + m * 2048 + k * 1024); } while (0)
; #define PG8_MMA(ai, bj, At, Bt) do { __builtin_amdgcn_s_setprio(1); _Pragma("unroll") for (int m = 0; m < 4; ++m) _Pragma("unroll") for (int n = 0; n < 2; ++n) _Pragma("unroll") for (int k = 0; k < 2; ++k) \
;         acc[ai][bj][m][n] = __builtin_amdgcn_mfma_f32_16x16x32_bf16(Bt[n][k], At[m][k], acc[ai][bj][m][n], 0, 0, 0); __builtin_amdgcn_s_setprio(0); } while (0)
; #define PG8_WAIT_V(n) asm volatile("s_waitcnt vmcnt(" #n ")" ::: "memory")
; #define PG8_WAIT_L(n) asm volatile("s_waitcnt lgkmcnt(" #n ")" ::: "memory")
; #define PG8_BAR __builtin_amdgcn_s_barrier()
; #define PG8_SCHED __builtin_amdgcn_sched_barrier(0)
;     __device__ __forceinline__ void operator()(const f32x4 (&acc)[2][2][4][2], const Unit& u, int wr, int wc, int fr, int fq) const {
;         const int row0 = u.pm * BM + wr * 64 + fr; const int col0 = u.pn * HALF + wc * 32 + 8 * fq;
; #pragma unroll
;         for (int ai = 0; ai < 2; ++ai)
; #pragma unroll
;             for (int m = 0; m < 4; ++m) { const int row = row0 + ai * HALF + m * 16;
;                 const float sc = rstd_from_slots(slots, row, fq);
;                 const f32x4 g0 = acc[ai][0][m][0] * sc, g1 = acc[ai][0][m][1] * sc, u0 = acc[ai][1][m][0] * sc, u1 = acc[ai][1][m][1] * sc;
; template <class Epi, class Sched, bool ALIGN_EPI = false, bool SP2 = false>
; __device__ __forceinline__ void gemm_phase(PG8_LAS unsigned char* lds, const Gemm g, const Sched& S, const Epi& E) {
;     ...
;             PG8_WAIT_V(8); PG8_WAIT_L(0); PG8_BAR; PG8_MMA(0, 0, At, B0); PG8_MMA(0, 1, At, B1); PG8_BAR; PG8_SCHED;
;             PG8_LDA(At, 1, 1); PG8_STAGE(PG8_SB(1, 0), b3, voffB); PG8_STAGE(PG8_SB(1, 1), b3 + hstepB, voffB); PG8_STAGE(PG8_SA(1, 0), a3, voffA);
;             PG8_WAIT_V(8); PG8_WAIT_L(0); PG8_BAR; PG8_MMA(1, 0, At, B0); PG8_MMA(1, 1, At, B1); PG8_BAR; PG8_SCHED;
.Lnoslot_P12:
	s_barrier
	s_waitcnt lgkmcnt(0)
	v_mfma_f32_16x16x32_bf16 v[60:63], v[146:149], v[190:193], v[60:63]
	v_mfma_f32_16x16x32_bf16 v[56:59], v[166:169], v[190:193], v[56:59]
	v_mfma_f32_16x16x32_bf16 v[44:47], v[146:149], v[198:201], v[44:47]
	v_mfma_f32_16x16x32_bf16 v[40:43], v[166:169], v[198:201], v[40:43]
	v_mfma_f32_16x16x32_bf16 v[28:31], v[146:149], v[206:209], v[28:31]
	v_mfma_f32_16x16x32_bf16 v[24:27], v[166:169], v[206:209], v[24:27]
	v_mfma_f32_16x16x32_bf16 v[12:15], v[146:149], v[214:217], v[12:15]
	v_mfma_f32_16x16x32_bf16 v[8:11], v[166:169], v[214:217], v[8:11]
	v_mfma_f32_16x16x32_bf16 v[60:63], v[162:165], v[194:197], v[60:63]
	v_mfma_f32_16x16x32_bf16 v[56:59], v[170:173], v[194:197], v[56:59]
	v_mfma_f32_16x16x32_bf16 v[44:47], v[162:165], v[202:205], v[44:47]
	v_mfma_f32_16x16x32_bf16 v[40:43], v[170:173], v[202:205], v[40:43]
	v_mfma_f32_16x16x32_bf16 v[28:31], v[162:165], v[210:213], v[28:31]
	v_mfma_f32_16x16x32_bf16 v[24:27], v[170:173], v[210:213], v[24:27]
	v_mfma_f32_16x16x32_bf16 v[12:15], v[162:165], v[218:221], v[12:15]
	v_mfma_f32_16x16x32_bf16 v[8:11], v[170:173], v[218:221], v[8:11]
	v_mfma_f32_16x16x32_bf16 v[52:55], v[174:177], v[190:193], v[52:55]
	v_mfma_f32_16x16x32_bf16 v[48:51], v[182:185], v[190:193], v[48:51]
	v_mfma_f32_16x16x32_bf16 v[36:39], v[174:177], v[198:201], v[36:39]
	v_mfma_f32_16x16x32_bf16 v[32:35], v[182:185], v[198:201], v[32:35]
	v_mfma_f32_16x16x32_bf16 v[20:23], v[174:177], v[206:209], v[20:23]
	v_mfma_f32_16x16x32_bf16 v[16:19], v[182:185], v[206:209], v[16:19]
	v_mfma_f32_16x16x32_bf16 v[4:7], v[174:177], v[214:217], v[4:7]
	v_mfma_f32_16x16x32_bf16 v[0:3], v[182:185], v[214:217], v[0:3]
	v_mfma_f32_16x16x32_bf16 v[52:55], v[178:181], v[194:197], v[52:55]
	v_mfma_f32_16x16x32_bf16 v[48:51], v[186:189], v[194:197], v[48:51]
	v_mfma_f32_16x16x32_bf16 v[36:39], v[178:181], v[202:205], v[36:39]
	v_mfma_f32_16x16x32_bf16 v[32:35], v[186:189], v[202:205], v[32:35]
	v_mfma_f32_16x16x32_bf16 v[20:23], v[178:181], v[210:213], v[20:23]
	v_mfma_f32_16x16x32_bf16 v[16:19], v[186:189], v[210:213], v[16:19]
	v_mfma_f32_16x16x32_bf16 v[4:7], v[178:181], v[218:221], v[4:7]
	v_mfma_f32_16x16x32_bf16 v[0:3], v[186:189], v[218:221], v[0:3]
	s_barrier
	s_add_i32 s28, s28, 2
	s_add_u32 s20, s20, 0x100
	s_addc_u32 s21, s21, 0
	s_add_u32 s26, s26, 0x100
	s_addc_u32 s27, s27, 0
	s_cmp_gt_u32 s28, 13
	s_cbranch_scc0 .LBB0_1111
	v_add_co_u32_e32 v206, vcc, 0x2000, v232
	s_nop 1
	v_addc_co_u32_e32 v207, vcc, 0, v233, vcc
	global_load_dwordx4 v[188:191], v[206:207], off
	global_load_dwordx4 v[192:195], v[206:207], off offset:1024
	global_load_dwordx4 v[196:199], v[206:207], off offset:2048
	global_load_dwordx4 v[200:203], v[206:207], off offset:3072
	s_and_b64 vcc, exec, s[12:13]
	s_cbranch_vccz .LBB0_1114
	s_barrier
.LBB0_1114:
	v_xor_b32_e32 v216, 16, v160
	v_xor_b32_e32 v217, 32, v160
	v_lshlrev_b32_e32 v216, 2, v216
	v_lshlrev_b32_e32 v217, 2, v217
	v_lshl_add_u32 v150, s0, 8, v152
	v_lshl_or_b32 v148, s1, 7, v156
	v_mov_b64_e32 v[146:147], s[10:11]
	v_ashrrev_i32_e32 v149, 31, v148
	v_lshlrev_b64 v[148:149], 1, v[148:149]
	s_andn2_b64 vcc, exec, s[2:3]
	v_mad_i64_i32 v[164:165], s[0:1], v150, s56, v[146:147]
	v_lshl_add_u64 v[164:165], v[164:165], 0, v[148:149]
	s_mov_b64 s[0:1], -1
	s_mov_b32 s98, 0x16000
	s_mov_b32 s99, 0
	v_pk_mul_f32 v[112:113], v[120:121], v[112:113]
	v_pk_mul_f32 v[114:115], v[122:123], v[114:115]
	v_pk_mul_f32 v[116:117], v[124:125], v[116:117]
	v_pk_mul_f32 v[118:119], v[126:127], v[118:119]
	v_pk_mul_f32 v[96:97], v[104:105], v[96:97]
	v_pk_mul_f32 v[98:99], v[106:107], v[98:99]
	v_pk_mul_f32 v[100:101], v[108:109], v[100:101]
	v_pk_mul_f32 v[102:103], v[110:111], v[102:103]
	v_pk_mul_f32 v[80:81], v[88:89], v[80:81]
	v_pk_mul_f32 v[82:83], v[90:91], v[82:83]
	v_pk_mul_f32 v[84:85], v[92:93], v[84:85]
	v_pk_mul_f32 v[86:87], v[94:95], v[86:87]
	v_pk_mul_f32 v[64:65], v[72:73], v[64:65]
	v_pk_mul_f32 v[66:67], v[74:75], v[66:67]
	v_pk_mul_f32 v[68:69], v[76:77], v[68:69]
	v_pk_mul_f32 v[70:71], v[78:79], v[70:71]
	v_pk_mul_f32 v[48:49], v[56:57], v[48:49]
	v_pk_mul_f32 v[50:51], v[58:59], v[50:51]
	v_pk_mul_f32 v[52:53], v[60:61], v[52:53]
	v_pk_mul_f32 v[54:55], v[62:63], v[54:55]
	v_pk_mul_f32 v[32:33], v[40:41], v[32:33]
	v_pk_mul_f32 v[34:35], v[42:43], v[34:35]
	v_pk_mul_f32 v[36:37], v[44:45], v[36:37]
	v_pk_mul_f32 v[38:39], v[46:47], v[38:39]
	v_pk_mul_f32 v[16:17], v[24:25], v[16:17]
	v_pk_mul_f32 v[18:19], v[26:27], v[18:19]
	v_pk_mul_f32 v[20:21], v[28:29], v[20:21]
	v_pk_mul_f32 v[22:23], v[30:31], v[22:23]
	v_pk_mul_f32 v[0:1], v[8:9], v[0:1]
	v_pk_mul_f32 v[2:3], v[10:11], v[2:3]
	v_pk_mul_f32 v[4:5], v[12:13], v[4:5]
	v_pk_mul_f32 v[6:7], v[14:15], v[6:7]
	s_waitcnt vmcnt(4)
	v_add_f32_e32 v240, v240, v241
	v_add_f32_e32 v244, v244, v245
	v_add_f32_e32 v248, v248, v249
	v_add_f32_e32 v252, v252, v253
	v_add_f32_e32 v241, v243, v242
	v_add_f32_e32 v245, v247, v246
	v_add_f32_e32 v249, v251, v250
	v_add_f32_e32 v253, v255, v254
	v_add_f32_e32 v240, v240, v241
	v_add_f32_e32 v244, v244, v245
	v_add_f32_e32 v248, v248, v249
	v_add_f32_e32 v252, v252, v253
	ds_bpermute_b32 v241, v216, v240
	ds_bpermute_b32 v245, v216, v244
	ds_bpermute_b32 v249, v216, v248
	ds_bpermute_b32 v253, v216, v252
	s_waitcnt lgkmcnt(0)
	v_add_f32_e32 v240, v240, v241
	v_add_f32_e32 v244, v244, v245
	v_add_f32_e32 v248, v248, v249
	v_add_f32_e32 v252, v252, v253
	ds_bpermute_b32 v241, v217, v240
	ds_bpermute_b32 v245, v217, v244
	ds_bpermute_b32 v249, v217, v248
	ds_bpermute_b32 v253, v217, v252
	s_waitcnt lgkmcnt(0)
; __device__ __forceinline__ unsigned cvt_pk_bf16(float lo, float hi) { const cvt_f32x2_t v = {lo, hi}; const cvt_bf16x2_t b = __builtin_convertvector(v, cvt_bf16x2_t); return __builtin_bit_cast(unsigned, b); }
; __device__ __forceinline__ float rstd_from_slots(const float* slots, int row, int fq) {
;     const f32x4 s4 = *(const f32x4*)(slots + (size_t)row * 16 + 4 * fq);
;     float s = (s4[0] + s4[1]) + (s4[2] + s4[3]);
;     s += __shfl_xor(s, 16); s += __shfl_xor(s, 32);
;     return __builtin_amdgcn_rsqf(s * (1.0f / 1024.0f) + RMS_EPS_F);
; __device__ __forceinline__ float silu_mul(float g, float u) { return g * u * __builtin_amdgcn_rcpf(1.0f + __builtin_amdgcn_exp2f(g * -1.4426950408889634f)); }
;     __device__ __forceinline__ void operator()(const f32x4 (&acc)[2][2][4][2], const Unit& u, int wr, int wc, int fr, int fq) const {
;         const int row0 = u.pm * BM + wr * 64 + fr; const int col0 = u.pn * HALF + wc * 32 + 8 * fq;
; #pragma unroll
;         for (int ai = 0; ai < 2; ++ai)
; #pragma unroll
;             for (int m = 0; m < 4; ++m) { const int row = row0 + ai * HALF + m * 16;
;                 const float sc = rstd_from_slots(slots, row, fq);
;                 const f32x4 g0 = acc[ai][0][m][0] * sc, g1 = acc[ai][0][m][1] * sc, u0 = acc[ai][1][m][0] * sc, u1 = acc[ai][1][m][1] * sc;
;                 u32x4 w; w.x = cvt_pk_bf16(silu_mul(g0[0], u0[0]), silu_mul(g0[1], u0[1])); w.y = cvt_pk_bf16(silu_mul(g0[2], u0[2]), silu_mul(g0[3], u0[3]));
;                 w.z = cvt_pk_bf16(silu_mul(g1[0], u1[0]), silu_mul(g1[1], u1[1])); w.w = cvt_pk_bf16(silu_mul(g1[2], u1[2]), silu_mul(g1[3], u1[3]));
;                 __builtin_nontemporal_store(w, (u32x4*)(O + (size_t)row * ldc + col0)); }
	v_add_f32_e32 v240, v240, v241
	v_add_f32_e32 v244, v244, v245
	v_add_f32_e32 v248, v248, v249
	v_add_f32_e32 v252, v252, v253
	v_fmamk_f32 v241, v240, 0x3a800000, v161
	v_fmamk_f32 v245, v244, 0x3a800000, v161
	v_fmamk_f32 v249, v248, 0x3a800000, v161
	v_fmamk_f32 v253, v252, 0x3a800000, v161
	v_rsq_f32_e32 v240, v241
	v_rsq_f32_e32 v244, v245
	v_rsq_f32_e32 v248, v249
	v_rsq_f32_e32 v252, v253
	s_nop 0
	v_mul_f32_e32 v240, 0xbfb8aa3b, v240
	v_mul_f32_e32 v244, 0xbfb8aa3b, v244
	v_mul_f32_e32 v248, 0xbfb8aa3b, v248
	v_mul_f32_e32 v252, 0xbfb8aa3b, v252
	v_mul_f32_e32 v120, v240, v120
	v_mul_f32_e32 v121, v240, v121
	v_mul_f32_e32 v122, v240, v122
	v_mul_f32_e32 v123, v240, v123
	v_mul_f32_e32 v124, v240, v124
	v_mul_f32_e32 v125, v240, v125
	v_mul_f32_e32 v126, v240, v126
	v_mul_f32_e32 v127, v240, v127
	v_exp_f32_e32 v120, v120
	v_exp_f32_e32 v121, v121
	v_exp_f32_e32 v122, v122
	v_exp_f32_e32 v123, v123
	v_exp_f32_e32 v124, v124
	v_exp_f32_e32 v125, v125
	v_exp_f32_e32 v126, v126
	v_exp_f32_e32 v127, v127
	v_fma_f32 v120, v120, v241, v241
	v_fma_f32 v121, v121, v241, v241
	v_fma_f32 v122, v122, v241, v241
	v_fma_f32 v123, v123, v241, v241
	v_fma_f32 v124, v124, v241, v241
	v_fma_f32 v125, v125, v241, v241
	v_fma_f32 v126, v126, v241, v241
	v_fma_f32 v127, v127, v241, v241
	v_rcp_f32_e32 v120, v120
	v_rcp_f32_e32 v121, v121
	v_rcp_f32_e32 v122, v122
	v_rcp_f32_e32 v123, v123
	v_rcp_f32_e32 v124, v124
	v_rcp_f32_e32 v125, v125
	v_rcp_f32_e32 v126, v126
	v_rcp_f32_e32 v127, v127
	v_pk_mul_f32 v[112:113], v[112:113], v[120:121]
	v_pk_mul_f32 v[114:115], v[114:115], v[122:123]
	v_pk_mul_f32 v[116:117], v[116:117], v[124:125]
	v_pk_mul_f32 v[118:119], v[118:119], v[126:127]
	v_cvt_pk_bf16_f32 v120, v116, v117
	v_cvt_pk_bf16_f32 v121, v118, v119
	v_cvt_pk_bf16_f32 v122, v112, v113
	v_cvt_pk_bf16_f32 v123, v114, v115
	global_store_dwordx4 v[164:165], v[120:123], off nt
	v_lshl_add_u64 v[166:167], v[164:165], 0, s[98:99]
	v_mul_f32_e32 v104, v244, v104
	v_mul_f32_e32 v105, v244, v105
	v_mul_f32_e32 v106, v244, v106
	v_mul_f32_e32 v107, v244, v107
	v_mul_f32_e32 v108, v244, v108
	v_mul_f32_e32 v109, v244, v109
	v_mul_f32_e32 v110, v244, v110
	v_mul_f32_e32 v111, v244, v111
	v_exp_f32_e32 v104, v104
	v_exp_f32_e32 v105, v105
	v_exp_f32_e32 v106, v106
	v_exp_f32_e32 v107, v107
	v_exp_f32_e32 v108, v108
	v_exp_f32_e32 v109, v109
	v_exp_f32_e32 v110, v110
	v_exp_f32_e32 v111, v111
	v_fma_f32 v104, v104, v245, v245
	v_fma_f32 v105, v105, v245, v245
	v_fma_f32 v106, v106, v245, v245
	v_fma_f32 v107, v107, v245, v245
	v_fma_f32 v108, v108, v245, v245
	v_fma_f32 v109, v109, v245, v245
	v_fma_f32 v110, v110, v245, v245
	v_fma_f32 v111, v111, v245, v245
	v_rcp_f32_e32 v104, v104
	v_rcp_f32_e32 v105, v105
	v_rcp_f32_e32 v106, v106
	v_rcp_f32_e32 v107, v107
	v_rcp_f32_e32 v108, v108
	v_rcp_f32_e32 v109, v109
	v_rcp_f32_e32 v110, v110
	v_rcp_f32_e32 v111, v111
	v_pk_mul_f32 v[96:97], v[96:97], v[104:105]
	v_pk_mul_f32 v[98:99], v[98:99], v[106:107]
	v_pk_mul_f32 v[100:101], v[100:101], v[108:109]
	v_pk_mul_f32 v[102:103], v[102:103], v[110:111]
	v_cvt_pk_bf16_f32 v104, v100, v101
	v_cvt_pk_bf16_f32 v105, v102, v103
	v_cvt_pk_bf16_f32 v106, v96, v97
	v_cvt_pk_bf16_f32 v107, v98, v99
	global_store_dwordx4 v[166:167], v[104:107], off nt
	v_lshl_add_u64 v[164:165], v[166:167], 0, s[98:99]
	v_mul_f32_e32 v88, v248, v88
	v_mul_f32_e32 v89, v248, v89
	v_mul_f32_e32 v90, v248, v90
	v_mul_f32_e32 v91, v248, v91
	v_mul_f32_e32 v92, v248, v92
	v_mul_f32_e32 v93, v248, v93
	v_mul_f32_e32 v94, v248, v94
	v_mul_f32_e32 v95, v248, v95
	v_exp_f32_e32 v88, v88
	v_exp_f32_e32 v89, v89
	v_exp_f32_e32 v90, v90
	v_exp_f32_e32 v91, v91
	v_exp_f32_e32 v92, v92
	v_exp_f32_e32 v93, v93
	v_exp_f32_e32 v94, v94
	v_exp_f32_e32 v95, v95
	v_fma_f32 v88, v88, v249, v249
	v_fma_f32 v89, v89, v249, v249
	v_fma_f32 v90, v90, v249, v249
	v_fma_f32 v91, v91, v249, v249
	v_fma_f32 v92, v92, v249, v249
	v_fma_f32 v93, v93, v249, v249
	v_fma_f32 v94, v94, v249, v249
	v_fma_f32 v95, v95, v249, v249
	v_rcp_f32_e32 v88, v88
	v_rcp_f32_e32 v89, v89
	v_rcp_f32_e32 v90, v90
	v_rcp_f32_e32 v91, v91
	v_rcp_f32_e32 v92, v92
	v_rcp_f32_e32 v93, v93
	v_rcp_f32_e32 v94, v94
	v_rcp_f32_e32 v95, v95
	v_pk_mul_f32 v[80:81], v[80:81], v[88:89]
	v_pk_mul_f32 v[82:83], v[82:83], v[90:91]
	v_pk_mul_f32 v[84:85], v[84:85], v[92:93]
	v_pk_mul_f32 v[86:87], v[86:87], v[94:95]
	v_cvt_pk_bf16_f32 v88, v84, v85
	v_cvt_pk_bf16_f32 v89, v86, v87
	v_cvt_pk_bf16_f32 v90, v80, v81
	v_cvt_pk_bf16_f32 v91, v82, v83
	global_store_dwordx4 v[164:165], v[88:91], off nt
	v_lshl_add_u64 v[166:167], v[164:165], 0, s[98:99]
	v_mul_f32_e32 v72, v252, v72
	v_mul_f32_e32 v73, v252, v73
	v_mul_f32_e32 v74, v252, v74
	v_mul_f32_e32 v75, v252, v75
	v_mul_f32_e32 v76, v252, v76
	v_mul_f32_e32 v77, v252, v77
	v_mul_f32_e32 v78, v252, v78
	v_mul_f32_e32 v79, v252, v79
	v_exp_f32_e32 v72, v72
	v_exp_f32_e32 v73, v73
	v_exp_f32_e32 v74, v74
	v_exp_f32_e32 v75, v75
	v_exp_f32_e32 v76, v76
	v_exp_f32_e32 v77, v77
	v_exp_f32_e32 v78, v78
	v_exp_f32_e32 v79, v79
	v_fma_f32 v72, v72, v253, v253
	v_fma_f32 v73, v73, v253, v253
	v_fma_f32 v74, v74, v253, v253
	v_fma_f32 v75, v75, v253, v253
	v_fma_f32 v76, v76, v253, v253
	v_fma_f32 v77, v77, v253, v253
	v_fma_f32 v78, v78, v253, v253
	v_fma_f32 v79, v79, v253, v253
	v_rcp_f32_e32 v72, v72
	v_rcp_f32_e32 v73, v73
	v_rcp_f32_e32 v74, v74
	v_rcp_f32_e32 v75, v75
	v_rcp_f32_e32 v76, v76
	v_rcp_f32_e32 v77, v77
	v_rcp_f32_e32 v78, v78
	v_rcp_f32_e32 v79, v79
	v_pk_mul_f32 v[64:65], v[64:65], v[72:73]
	v_pk_mul_f32 v[66:67], v[66:67], v[74:75]
	v_pk_mul_f32 v[68:69], v[68:69], v[76:77]
	v_pk_mul_f32 v[70:71], v[70:71], v[78:79]
	v_cvt_pk_bf16_f32 v72, v68, v69
	v_cvt_pk_bf16_f32 v73, v70, v71
	v_cvt_pk_bf16_f32 v74, v64, v65
	v_cvt_pk_bf16_f32 v75, v66, v67
	global_store_dwordx4 v[166:167], v[72:75], off nt
	s_waitcnt vmcnt(4)
; __device__ __forceinline__ unsigned cvt_pk_bf16(float lo, float hi) { const cvt_f32x2_t v = {lo, hi}; const cvt_bf16x2_t b = __builtin_convertvector(v, cvt_bf16x2_t); return __builtin_bit_cast(unsigned, b); }
; __device__ __forceinline__ float rstd_from_slots(const float* slots, int row, int fq) {
;     const f32x4 s4 = *(const f32x4*)(slots + (size_t)row * 16 + 4 * fq);
;     float s = (s4[0] + s4[1]) + (s4[2] + s4[3]);
;     s += __shfl_xor(s, 16); s += __shfl_xor(s, 32);
;     return __builtin_amdgcn_rsqf(s * (1.0f / 1024.0f) + RMS_EPS_F);
; __device__ __forceinline__ float silu_mul(float g, float u) { return g * u * __builtin_amdgcn_rcpf(1.0f + __builtin_amdgcn_exp2f(g * -1.4426950408889634f)); }
;     __device__ __forceinline__ void operator()(const f32x4 (&acc)[2][2][4][2], const Unit& u, int wr, int wc, int fr, int fq) const {
;         const int row0 = u.pm * BM + wr * 64 + fr; const int col0 = u.pn * HALF + wc * 32 + 8 * fq;
; #pragma unroll
;         for (int ai = 0; ai < 2; ++ai)
; #pragma unroll
;             for (int m = 0; m < 4; ++m) { const int row = row0 + ai * HALF + m * 16;
;                 const float sc = rstd_from_slots(slots, row, fq);
;                 const f32x4 g0 = acc[ai][0][m][0] * sc, g1 = acc[ai][0][m][1] * sc, u0 = acc[ai][1][m][0] * sc, u1 = acc[ai][1][m][1] * sc;
;                 u32x4 w; w.x = cvt_pk_bf16(silu_mul(g0[0], u0[0]), silu_mul(g0[1], u0[1])); w.y = cvt_pk_bf16(silu_mul(g0[2], u0[2]), silu_mul(g0[3], u0[3]));
;                 w.z = cvt_pk_bf16(silu_mul(g1[0], u1[0]), silu_mul(g1[1], u1[1])); w.w = cvt_pk_bf16(silu_mul(g1[2], u1[2]), silu_mul(g1[3], u1[3]));
;                 __builtin_nontemporal_store(w, (u32x4*)(O + (size_t)row * ldc + col0)); }
	v_add_f32_e32 v188, v188, v189
	v_add_f32_e32 v192, v192, v193
	v_add_f32_e32 v196, v196, v197
	v_add_f32_e32 v200, v200, v201
	v_add_f32_e32 v189, v191, v190
	v_add_f32_e32 v193, v195, v194
	v_add_f32_e32 v197, v199, v198
	v_add_f32_e32 v201, v203, v202
	v_add_f32_e32 v188, v188, v189
	v_add_f32_e32 v192, v192, v193
	v_add_f32_e32 v196, v196, v197
	v_add_f32_e32 v200, v200, v201
	ds_bpermute_b32 v189, v216, v188
	ds_bpermute_b32 v193, v216, v192
	ds_bpermute_b32 v197, v216, v196
	ds_bpermute_b32 v201, v216, v200
	s_waitcnt lgkmcnt(0)
	v_add_f32_e32 v188, v188, v189
	v_add_f32_e32 v192, v192, v193
	v_add_f32_e32 v196, v196, v197
	v_add_f32_e32 v200, v200, v201
	ds_bpermute_b32 v189, v217, v188
	ds_bpermute_b32 v193, v217, v192
	ds_bpermute_b32 v197, v217, v196
	ds_bpermute_b32 v201, v217, v200
	s_waitcnt lgkmcnt(0)
	v_add_f32_e32 v188, v188, v189
	v_add_f32_e32 v192, v192, v193
	v_add_f32_e32 v196, v196, v197
	v_add_f32_e32 v200, v200, v201
	v_fmamk_f32 v189, v188, 0x3a800000, v161
	v_fmamk_f32 v193, v192, 0x3a800000, v161
	v_fmamk_f32 v197, v196, 0x3a800000, v161
	v_fmamk_f32 v201, v200, 0x3a800000, v161
	v_rsq_f32_e32 v188, v189
	v_rsq_f32_e32 v192, v193
	v_rsq_f32_e32 v196, v197
	v_rsq_f32_e32 v200, v201
	s_nop 0
	v_mul_f32_e32 v188, 0xbfb8aa3b, v188
	v_mul_f32_e32 v192, 0xbfb8aa3b, v192
	v_mul_f32_e32 v196, 0xbfb8aa3b, v196
	v_mul_f32_e32 v200, 0xbfb8aa3b, v200
	s_mov_b32 s98, 0x6e000
	v_lshl_add_u64 v[164:165], v[166:167], 0, s[98:99]
	s_mov_b32 s98, 0x16000
	v_mul_f32_e32 v56, v188, v56
	v_mul_f32_e32 v57, v188, v57
	v_mul_f32_e32 v58, v188, v58
	v_mul_f32_e32 v59, v188, v59
	v_mul_f32_e32 v60, v188, v60
	v_mul_f32_e32 v61, v188, v61
	v_mul_f32_e32 v62, v188, v62
	v_mul_f32_e32 v63, v188, v63
	v_exp_f32_e32 v56, v56
	v_exp_f32_e32 v57, v57
	v_exp_f32_e32 v58, v58
	v_exp_f32_e32 v59, v59
	v_exp_f32_e32 v60, v60
	v_exp_f32_e32 v61, v61
	v_exp_f32_e32 v62, v62
	v_exp_f32_e32 v63, v63
	v_fma_f32 v56, v56, v189, v189
	v_fma_f32 v57, v57, v189, v189
	v_fma_f32 v58, v58, v189, v189
	v_fma_f32 v59, v59, v189, v189
	v_fma_f32 v60, v60, v189, v189
	v_fma_f32 v61, v61, v189, v189
	v_fma_f32 v62, v62, v189, v189
	v_fma_f32 v63, v63, v189, v189
	v_rcp_f32_e32 v56, v56
	v_rcp_f32_e32 v57, v57
	v_rcp_f32_e32 v58, v58
	v_rcp_f32_e32 v59, v59
	v_rcp_f32_e32 v60, v60
	v_rcp_f32_e32 v61, v61
	v_rcp_f32_e32 v62, v62
	v_rcp_f32_e32 v63, v63
	v_pk_mul_f32 v[48:49], v[48:49], v[56:57]
	v_pk_mul_f32 v[50:51], v[50:51], v[58:59]
	v_pk_mul_f32 v[52:53], v[52:53], v[60:61]
	v_pk_mul_f32 v[54:55], v[54:55], v[62:63]
	v_cvt_pk_bf16_f32 v56, v52, v53
	v_cvt_pk_bf16_f32 v57, v54, v55
	v_cvt_pk_bf16_f32 v58, v48, v49
	v_cvt_pk_bf16_f32 v59, v50, v51
	global_store_dwordx4 v[164:165], v[56:59], off nt
	v_lshl_add_u64 v[166:167], v[164:165], 0, s[98:99]
	v_mul_f32_e32 v40, v192, v40
	v_mul_f32_e32 v41, v192, v41
	v_mul_f32_e32 v42, v192, v42
	v_mul_f32_e32 v43, v192, v43
	v_mul_f32_e32 v44, v192, v44
	v_mul_f32_e32 v45, v192, v45
	v_mul_f32_e32 v46, v192, v46
	v_mul_f32_e32 v47, v192, v47
	v_exp_f32_e32 v40, v40
	v_exp_f32_e32 v41, v41
	v_exp_f32_e32 v42, v42
	v_exp_f32_e32 v43, v43
	v_exp_f32_e32 v44, v44
	v_exp_f32_e32 v45, v45
	v_exp_f32_e32 v46, v46
	v_exp_f32_e32 v47, v47
	v_fma_f32 v40, v40, v193, v193
	v_fma_f32 v41, v41, v193, v193
	v_fma_f32 v42, v42, v193, v193
	v_fma_f32 v43, v43, v193, v193
	v_fma_f32 v44, v44, v193, v193
	v_fma_f32 v45, v45, v193, v193
	v_fma_f32 v46, v46, v193, v193
	v_fma_f32 v47, v47, v193, v193
	v_rcp_f32_e32 v40, v40
	v_rcp_f32_e32 v41, v41
	v_rcp_f32_e32 v42, v42
	v_rcp_f32_e32 v43, v43
	v_rcp_f32_e32 v44, v44
	v_rcp_f32_e32 v45, v45
	v_rcp_f32_e32 v46, v46
	v_rcp_f32_e32 v47, v47
	v_pk_mul_f32 v[32:33], v[32:33], v[40:41]
	v_pk_mul_f32 v[34:35], v[34:35], v[42:43]
	v_pk_mul_f32 v[36:37], v[36:37], v[44:45]
	v_pk_mul_f32 v[38:39], v[38:39], v[46:47]
	v_cvt_pk_bf16_f32 v40, v36, v37
	v_cvt_pk_bf16_f32 v41, v38, v39
	v_cvt_pk_bf16_f32 v42, v32, v33
	v_cvt_pk_bf16_f32 v43, v34, v35
	global_store_dwordx4 v[166:167], v[40:43], off nt
	v_lshl_add_u64 v[164:165], v[166:167], 0, s[98:99]
	v_mul_f32_e32 v24, v196, v24
	v_mul_f32_e32 v25, v196, v25
	v_mul_f32_e32 v26, v196, v26
	v_mul_f32_e32 v27, v196, v27
	v_mul_f32_e32 v28, v196, v28
	v_mul_f32_e32 v29, v196, v29
	v_mul_f32_e32 v30, v196, v30
	v_mul_f32_e32 v31, v196, v31
	v_exp_f32_e32 v24, v24
	v_exp_f32_e32 v25, v25
	v_exp_f32_e32 v26, v26
	v_exp_f32_e32 v27, v27
	v_exp_f32_e32 v28, v28
	v_exp_f32_e32 v29, v29
	v_exp_f32_e32 v30, v30
	v_exp_f32_e32 v31, v31
	v_fma_f32 v24, v24, v197, v197
	v_fma_f32 v25, v25, v197, v197
	v_fma_f32 v26, v26, v197, v197
	v_fma_f32 v27, v27, v197, v197
	v_fma_f32 v28, v28, v197, v197
	v_fma_f32 v29, v29, v197, v197
	v_fma_f32 v30, v30, v197, v197
	v_fma_f32 v31, v31, v197, v197
	v_rcp_f32_e32 v24, v24
	v_rcp_f32_e32 v25, v25
	v_rcp_f32_e32 v26, v26
	v_rcp_f32_e32 v27, v27
	v_rcp_f32_e32 v28, v28
	v_rcp_f32_e32 v29, v29
	v_rcp_f32_e32 v30, v30
	v_rcp_f32_e32 v31, v31
	v_pk_mul_f32 v[16:17], v[16:17], v[24:25]
	v_pk_mul_f32 v[18:19], v[18:19], v[26:27]
	v_pk_mul_f32 v[20:21], v[20:21], v[28:29]
	v_pk_mul_f32 v[22:23], v[22:23], v[30:31]
	v_cvt_pk_bf16_f32 v24, v20, v21
	v_cvt_pk_bf16_f32 v25, v22, v23
	v_cvt_pk_bf16_f32 v26, v16, v17
	v_cvt_pk_bf16_f32 v27, v18, v19
	global_store_dwordx4 v[164:165], v[24:27], off nt
	v_lshl_add_u64 v[166:167], v[164:165], 0, s[98:99]
	v_mul_f32_e32 v8, v200, v8
	v_mul_f32_e32 v9, v200, v9
	v_mul_f32_e32 v10, v200, v10
	v_mul_f32_e32 v11, v200, v11
	v_mul_f32_e32 v12, v200, v12
	v_mul_f32_e32 v13, v200, v13
	v_mul_f32_e32 v14, v200, v14
	v_mul_f32_e32 v15, v200, v15
	v_exp_f32_e32 v8, v8
	v_exp_f32_e32 v9, v9
	v_exp_f32_e32 v10, v10
	v_exp_f32_e32 v11, v11
	v_exp_f32_e32 v12, v12
	v_exp_f32_e32 v13, v13
	v_exp_f32_e32 v14, v14
	v_exp_f32_e32 v15, v15
	v_fma_f32 v8, v8, v201, v201
	v_fma_f32 v9, v9, v201, v201
	v_fma_f32 v10, v10, v201, v201
	v_fma_f32 v11, v11, v201, v201
	v_fma_f32 v12, v12, v201, v201
	v_fma_f32 v13, v13, v201, v201
	v_fma_f32 v14, v14, v201, v201
	v_fma_f32 v15, v15, v201, v201
	v_rcp_f32_e32 v8, v8
	v_rcp_f32_e32 v9, v9
	v_rcp_f32_e32 v10, v10
	v_rcp_f32_e32 v11, v11
	v_rcp_f32_e32 v12, v12
	v_rcp_f32_e32 v13, v13
	v_rcp_f32_e32 v14, v14
	v_rcp_f32_e32 v15, v15
	v_pk_mul_f32 v[0:1], v[0:1], v[8:9]
	v_pk_mul_f32 v[2:3], v[2:3], v[10:11]
	v_pk_mul_f32 v[4:5], v[4:5], v[12:13]
	v_pk_mul_f32 v[6:7], v[6:7], v[14:15]
	v_cvt_pk_bf16_f32 v8, v4, v5
	v_cvt_pk_bf16_f32 v9, v6, v7
	v_cvt_pk_bf16_f32 v10, v0, v1
	v_cvt_pk_bf16_f32 v11, v2, v3
	global_store_dwordx4 v[166:167], v[8:11], off nt
	s_cbranch_vccnz .LBB0_1107
	s_andn2_b64 vcc, exec, s[6:7]
	s_cbranch_vccnz .LBB0_1106
	s_barrier
	s_branch .LBB0_1106
